# barrier release: four copies of each XCD generation word on different cache lines, 16 pollers per copy
# baseline (speedup 1.0000x reference)
.LBB0_5:
	s_or_b64 exec, exec, s[12:13]
	s_load_dwordx2 s[6:7], s[0:1], 0xd0
	s_waitcnt lgkmcnt(0)
	s_cmp_ge_i32 s6, s7
	s_cbranch_scc1 .LBB0_549
	s_add_u32 s10, s0, 0xd8
	s_addc_u32 s11, s1, 0
	v_writelane_b32 v252, s10, 2
	s_load_dwordx16 s[36:51], s[0:1], 0x0
	v_mbcnt_lo_u32_b32 v2, -1, 0
	v_writelane_b32 v252, s11, 3
	s_add_u32 s10, s62, 0x15e01200
	s_addc_u32 s11, s63, 0
	v_writelane_b32 v252, s10, 4
	s_mov_b32 s17, s6
	v_mov_b32_e32 v131, 0
	v_writelane_b32 v252, s11, 5
	s_add_u32 s10, s62, 0x15e01400
	s_addc_u32 s11, s63, 0
	v_writelane_b32 v252, s10, 6
	v_mov_b32_e32 v1, 1
	v_mov_b32_e32 v197, 0x358637bd
	v_writelane_b32 v252, s11, 7
	s_add_u32 s10, s62, 0x15e01500
	s_addc_u32 s11, s63, 0
	v_writelane_b32 v252, s10, 8
	v_mbcnt_hi_u32_b32 v198, -1, v2
	v_mov_b32_e32 v199, 0x3ff
	v_writelane_b32 v252, s11, 9
	s_add_u32 s10, s62, 0x15e01600
	s_addc_u32 s11, s63, 0
	v_writelane_b32 v252, s10, 10
	v_mov_b32_e32 v200, 0xc000
	v_mov_b32_e32 v203, 0x41b17218
	v_writelane_b32 v252, s11, 11
	s_add_u32 s10, s62, 0x15e01700
	s_addc_u32 s11, s63, 0
	v_writelane_b32 v252, s10, 12
	v_mov_b32_e32 v204, 0x6000
	s_movk_i32 s33, 0x1000
	v_writelane_b32 v252, s11, 13
	s_add_u32 s10, s62, 0x15e01800
	s_addc_u32 s11, s63, 0
	v_writelane_b32 v252, s10, 14
	s_movk_i32 s26, 0x7fff
	s_movk_i32 s85, 0x104
	v_writelane_b32 v252, s11, 15
	s_add_u32 s10, s62, 0x15e01900
	s_addc_u32 s11, s63, 0
	v_writelane_b32 v252, s10, 16
	s_movk_i32 s12, 0xc00
	s_movk_i32 s15, 0x28c0
	v_writelane_b32 v252, s11, 17
	s_add_u32 s10, s62, 0x15e01a00
	s_addc_u32 s11, s63, 0
	v_writelane_b32 v252, s10, 18
	s_mov_b32 s14, 0x800000
	s_mov_b32 s18, 0x3e38aa3b
	v_writelane_b32 v252, s11, 19
	s_add_u32 s10, s62, 0x15e01b00
	s_addc_u32 s11, s63, 0
	v_writelane_b32 v252, s10, 20
	s_mov_b32 s19, 0xffff0000
	s_movk_i32 s23, 0x110
	v_writelane_b32 v252, s11, 21
	s_add_u32 s10, s62, 0x15e01c00
	s_addc_u32 s11, s63, 0
	v_writelane_b32 v252, s10, 22
	s_mov_b32 s93, 0
	s_mov_b64 s[98:99], 0x80
	v_writelane_b32 v252, s11, 23
	s_add_u32 s10, s62, 0x15e01d00
	s_addc_u32 s11, s63, 0
	v_writelane_b32 v252, s10, 24
	s_mov_b64 s[70:71], 0x100
	s_mov_b64 s[72:73], 0x180
	v_writelane_b32 v252, s11, 25
	s_add_u32 s10, s62, 0x15e01e00
	s_addc_u32 s11, s63, 0
	v_writelane_b32 v252, s10, 26
	s_mov_b64 s[74:75], 0x200
	s_mov_b64 s[76:77], 0x280
	v_writelane_b32 v252, s11, 27
	s_add_u32 s10, s62, 0x15e01f00
	s_addc_u32 s11, s63, 0
	v_writelane_b32 v252, s10, 28
	s_mov_b64 s[78:79], 0x300
	s_mov_b64 s[80:81], 0x380
	v_writelane_b32 v252, s11, 29
	s_add_u32 s10, s62, 0x15e02000
	s_addc_u32 s11, s63, 0
	v_writelane_b32 v252, s10, 30
	s_mov_b64 s[90:91], 0x400
	s_mov_b64 s[82:83], 0x780
	v_writelane_b32 v252, s11, 31
	s_add_u32 s10, s62, 0x15e02100
	s_addc_u32 s11, s63, 0
	v_writelane_b32 v252, s10, 32
	s_nop 1
	v_writelane_b32 v252, s11, 33
	s_add_u32 s10, s62, 0x15e02200
	s_addc_u32 s11, s63, 0
	v_writelane_b32 v252, s10, 34
	s_nop 1
	v_writelane_b32 v252, s11, 35
	s_add_u32 s10, s62, 0x15e02300
	s_addc_u32 s11, s63, 0
	v_writelane_b32 v252, s10, 36
	s_cmp_eq_u32 s8, 15
	s_nop 0
	v_writelane_b32 v252, s11, 37
	s_cselect_b64 s[10:11], -1, 0
	v_writelane_b32 v252, s10, 38
	s_cmp_eq_u32 s8, 14
	s_nop 0
	v_writelane_b32 v252, s11, 39
	s_cselect_b64 s[10:11], -1, 0
	v_writelane_b32 v252, s10, 40
	s_cmp_eq_u32 s8, 13
	s_nop 0
	v_writelane_b32 v252, s11, 41
	s_cselect_b64 s[10:11], -1, 0
	v_writelane_b32 v252, s10, 42
	s_cmp_eq_u32 s8, 12
	s_nop 0
	v_writelane_b32 v252, s11, 43
	s_cselect_b64 s[10:11], -1, 0
	v_writelane_b32 v252, s10, 44
	s_cmp_eq_u32 s8, 11
	s_nop 0
	v_writelane_b32 v252, s11, 45
	s_cselect_b64 s[10:11], -1, 0
	v_writelane_b32 v252, s10, 46
	s_cmp_eq_u32 s8, 10
	s_nop 0
	v_writelane_b32 v252, s11, 47
	s_cselect_b64 s[10:11], -1, 0
	v_writelane_b32 v252, s10, 48
	s_cmp_eq_u32 s8, 9
	s_nop 0
	v_writelane_b32 v252, s11, 49
	s_cselect_b64 s[10:11], -1, 0
	v_writelane_b32 v252, s10, 50
	s_cmp_eq_u32 s8, 8
	s_nop 0
	v_writelane_b32 v252, s11, 51
	s_cselect_b64 s[10:11], -1, 0
	v_writelane_b32 v252, s10, 52
	s_cmp_eq_u32 s8, 7
	s_nop 0
	v_writelane_b32 v252, s11, 53
	s_cselect_b64 s[10:11], -1, 0
	v_writelane_b32 v252, s10, 54
	s_cmp_eq_u32 s8, 6
	s_nop 0
	v_writelane_b32 v252, s11, 55
	s_cselect_b64 s[10:11], -1, 0
	v_writelane_b32 v252, s10, 56
	s_cmp_eq_u32 s8, 5
	s_nop 0
	v_writelane_b32 v252, s11, 57
	s_cselect_b64 s[10:11], -1, 0
	v_writelane_b32 v252, s10, 58
	s_cmp_eq_u32 s8, 4
	s_nop 0
	v_writelane_b32 v252, s11, 59
	s_cselect_b64 s[10:11], -1, 0
	v_writelane_b32 v252, s10, 60
	s_cmp_eq_u32 s8, 3
	s_nop 0
	v_writelane_b32 v252, s11, 61
	s_cselect_b64 s[10:11], -1, 0
	v_writelane_b32 v252, s10, 62
	s_cmp_eq_u32 s8, 2
	s_nop 0
	v_writelane_b32 v252, s11, 63
	s_cselect_b64 s[10:11], -1, 0
	v_writelane_b32 v253, s10, 0
	s_cmp_eq_u32 s8, 1
	s_nop 0
	v_writelane_b32 v253, s11, 1
	s_cselect_b64 s[10:11], -1, 0
	v_writelane_b32 v253, s10, 2
	s_cmp_eq_u32 s8, 0
	s_nop 0
	v_writelane_b32 v253, s11, 3
	s_cselect_b64 s[10:11], -1, 0
	s_lshl_b32 s3, s8, 8
	s_add_u32 s4, s4, s3
	s_addc_u32 s3, s5, 0
	v_writelane_b32 v253, s10, 4
	s_add_u32 s8, s4, 0x1400
	s_addc_u32 s9, s3, 0
	v_writelane_b32 v253, s11, 5
	v_writelane_b32 v253, s8, 6
	s_add_u32 s4, s4, 0x2400
	s_addc_u32 s5, s3, 0
	v_writelane_b32 v253, s9, 7
	v_writelane_b32 v253, s4, 8
	s_nop 1
	v_writelane_b32 v253, s5, 9
	s_lshr_b32 s100, s2, 3
	s_and_b32 s100, s100, 3
	s_mov_b32 s101, 0
	s_cmp_eq_u32 s100, 1
	s_cselect_b32 s101, 0x80, s101
	s_cmp_eq_u32 s100, 2
	s_cselect_b32 s101, 0xfffff080, s101
	s_cmp_eq_u32 s100, 3
	s_cselect_b32 s101, 0xffffe080, s101
	s_ashr_i32 s100, s101, 31
	s_add_u32 s101, s4, s101
	s_addc_u32 s100, s5, s100
	s_nop 0
	v_writelane_b32 v255, s101, 53
	v_writelane_b32 v255, s100, 54
	s_add_u32 s4, s62, 0x15e04400
	s_addc_u32 s5, s63, 0
	v_writelane_b32 v253, s4, 10
	s_nop 1
	v_writelane_b32 v253, s5, 11
	s_add_u32 s4, s62, 0x15e04500
	s_addc_u32 s5, s63, 0
	v_writelane_b32 v253, s4, 12
	s_nop 1
	v_writelane_b32 v253, s5, 13
	s_add_u32 s4, s62, 0x80000
	s_addc_u32 s5, s63, 0
	v_writelane_b32 v253, s4, 14
	s_nop 1
	v_writelane_b32 v253, s5, 15
	s_add_u32 s4, s62, 0xf680000
	s_addc_u32 s5, s63, 0
	v_writelane_b32 v253, s4, 16
	s_nop 1
	v_writelane_b32 v253, s5, 17
	s_add_u32 s4, s62, 0xe680000
	s_addc_u32 s5, s63, 0
	s_add_u32 s8, s62, 0x2080000
	v_writelane_b32 v253, s4, 18
	s_addc_u32 s9, s63, 0
	s_nop 0
	v_writelane_b32 v253, s5, 19
	s_add_u32 s4, s62, 0x7e00000
	s_addc_u32 s5, s63, 0
	v_writelane_b32 v253, s4, 20
	s_nop 1
	v_writelane_b32 v253, s5, 21
	s_add_u32 s4, s62, 0x9e40000
	s_addc_u32 s5, s63, 0
	v_writelane_b32 v253, s4, 22
	s_nop 1
	v_writelane_b32 v253, s5, 23
	s_add_u32 s4, s62, 0xce80000
	s_addc_u32 s5, s63, 0
	v_writelane_b32 v253, s4, 24
	s_nop 1
	v_writelane_b32 v253, s5, 25
	s_add_u32 s4, s62, 0x1080000
	s_addc_u32 s5, s63, 0
	v_writelane_b32 v253, s4, 26
	s_nop 1
	v_writelane_b32 v253, s5, 27
	s_add_u32 s4, s62, 0xde80000
	s_addc_u32 s5, s63, 0
	s_add_u32 s68, s62, 0x9e80000
	v_writelane_b32 v253, s4, 28
	s_addc_u32 s69, s63, 0
	s_nop 0
	v_writelane_b32 v253, s5, 29
	s_add_u32 s4, s62, 0x9600000
	s_addc_u32 s5, s63, 0
	v_writelane_b32 v253, s4, 30
	s_nop 1
	v_writelane_b32 v253, s5, 31
	s_add_u32 s4, s62, 0x7200000
	s_addc_u32 s5, s63, 0
	v_writelane_b32 v253, s4, 32
	s_nop 1
	v_writelane_b32 v253, s5, 33
	s_add_u32 s4, s62, 0x7c00000
	s_addc_u32 s5, s63, 0
	v_writelane_b32 v253, s4, 34
	s_nop 1
	v_writelane_b32 v253, s5, 35
	s_add_u32 s4, s62, 0x15d81000
	s_addc_u32 s5, s63, 0
	v_writelane_b32 v253, s4, 36
	s_nop 1
	v_writelane_b32 v253, s5, 37
	s_add_u32 s4, s62, 0x15d01000
	s_addc_u32 s5, s63, 0
	v_writelane_b32 v253, s4, 38
	s_nop 1
	v_writelane_b32 v253, s5, 39
	s_add_u32 s4, s62, 0x7a00000
	s_addc_u32 s5, s63, 0
	v_writelane_b32 v253, s4, 40
	s_nop 1
	v_writelane_b32 v253, s5, 41
	s_add_u32 s4, s62, 0x154e0000
	s_addc_u32 s5, s63, 0
	v_writelane_b32 v253, s4, 42
	s_nop 1
	v_writelane_b32 v253, s5, 43
	s_add_u32 s4, s62, 0x15ce0000
	s_addc_u32 s5, s63, 0
	v_writelane_b32 v253, s4, 44
	s_add_u32 s3, s60, 0x3000000
	s_nop 0
	v_writelane_b32 v253, s5, 45
	v_writelane_b32 v253, s3, 46
	s_addc_u32 s3, s61, 0
	s_add_u32 s86, s62, 0x15d00000
	s_addc_u32 s87, s63, 0
	v_writelane_b32 v253, s3, 47
	s_add_u32 s3, s60, 0x3400000
	v_writelane_b32 v253, s3, 48
	s_addc_u32 s3, s61, 0
	s_add_u32 s4, s62, 0x9e00000
	v_writelane_b32 v253, s3, 49
	s_addc_u32 s5, s63, 0
	v_writelane_b32 v253, s4, 50
	s_nop 1
	v_writelane_b32 v253, s5, 51
	s_add_u32 s4, s60, 0x2000000
	s_addc_u32 s5, s61, 0
	v_writelane_b32 v253, s4, 52
	s_nop 1
	v_writelane_b32 v253, s5, 53
	s_add_u32 s4, s60, 0x2800000
	s_addc_u32 s5, s61, 0
	v_writelane_b32 v253, s4, 54
	s_nop 1
	v_writelane_b32 v253, s5, 55
	s_add_u32 s4, s62, 0x10898000
	s_addc_u32 s5, s63, 0
	v_writelane_b32 v253, s4, 56
	s_nop 1
	v_writelane_b32 v253, s5, 57
	s_add_u32 s4, s62, 0x10318000
	s_addc_u32 s5, s63, 0
	v_writelane_b32 v253, s4, 58
	s_nop 1
	v_writelane_b32 v253, s5, 59
	s_add_u32 s4, s62, 0xfd98000
	s_addc_u32 s5, s63, 0
	v_writelane_b32 v253, s4, 60
	s_nop 1
	v_writelane_b32 v253, s5, 61
	s_add_u32 s4, s62, 0xfb98000
	s_addc_u32 s5, s63, 0
	s_add_u32 s3, s62, 0x80
	v_writelane_b32 v254, s3, 0
	s_addc_u32 s3, s63, 0
	v_writelane_b32 v254, s3, 1
	s_add_u32 s3, s62, 0xf680080
	v_writelane_b32 v254, s3, 2
	s_addc_u32 s3, s63, 0
	v_writelane_b32 v254, s3, 3
	s_add_i32 s3, 0, 0x12ff0
	v_writelane_b32 v253, s4, 62
	v_writelane_b32 v254, s3, 4
	s_add_i32 s3, 0, 0x12ff4
	v_writelane_b32 v253, s5, 63
	v_writelane_b32 v254, s3, 5
	s_add_i32 s4, 0, 0x8200
	v_writelane_b32 v254, s4, 6
	s_add_i32 s4, 0, 0x10500
	v_writelane_b32 v254, s4, 7
	s_add_i32 s4, 0, 0x10700
	v_writelane_b32 v254, s4, 8
	s_add_i32 s4, 0, 0x10600
	v_writelane_b32 v254, s4, 9
	s_add_i32 s4, 0, 0x105fc
	v_writelane_b32 v254, s4, 10
	s_waitcnt lgkmcnt(0)
	v_writelane_b32 v254, s36, 11
	s_movk_i32 s3, 0x6000
	s_add_i32 s84, 0, 0x10400
	v_writelane_b32 v254, s37, 12
	v_writelane_b32 v254, s38, 13
	v_writelane_b32 v254, s39, 14
	v_writelane_b32 v254, s40, 15
	v_writelane_b32 v254, s41, 16
	v_writelane_b32 v254, s42, 17
	v_writelane_b32 v254, s43, 18
	v_writelane_b32 v254, s44, 19
	v_writelane_b32 v254, s45, 20
	v_writelane_b32 v254, s46, 21
	v_writelane_b32 v254, s47, 22
	v_writelane_b32 v254, s48, 23
	v_writelane_b32 v254, s49, 24
	v_writelane_b32 v254, s50, 25
	v_writelane_b32 v254, s51, 26
	s_load_dwordx16 s[36:51], s[0:1], 0x40
	s_waitcnt lgkmcnt(0)
	v_writelane_b32 v254, s36, 27
	s_nop 1
	v_writelane_b32 v254, s37, 28
	v_writelane_b32 v254, s38, 29
	v_writelane_b32 v254, s39, 30
	v_writelane_b32 v254, s40, 31
	v_writelane_b32 v254, s41, 32
	v_writelane_b32 v254, s42, 33
	v_writelane_b32 v254, s43, 34
	v_writelane_b32 v254, s44, 35
	v_writelane_b32 v254, s45, 36
	v_writelane_b32 v254, s46, 37
	v_writelane_b32 v254, s47, 38
	v_writelane_b32 v254, s48, 39
	v_writelane_b32 v254, s49, 40
	v_writelane_b32 v254, s50, 41
	v_writelane_b32 v254, s51, 42
	s_load_dwordx16 s[36:51], s[0:1], 0x80
	s_waitcnt lgkmcnt(0)
	v_writelane_b32 v254, s36, 43
	s_nop 1
	v_writelane_b32 v254, s37, 44
	v_writelane_b32 v254, s38, 45
	v_writelane_b32 v254, s39, 46
	v_writelane_b32 v254, s40, 47
	v_writelane_b32 v254, s41, 48
	v_writelane_b32 v254, s42, 49
	v_writelane_b32 v254, s43, 50
	v_writelane_b32 v254, s44, 51
	v_writelane_b32 v254, s45, 52
	v_writelane_b32 v254, s46, 53
	v_writelane_b32 v254, s47, 54
	v_writelane_b32 v254, s48, 55
	v_writelane_b32 v254, s49, 56
	v_writelane_b32 v254, s50, 57
	v_writelane_b32 v254, s51, 58
	v_writelane_b32 v254, s2, 59
	v_writelane_b32 v254, s6, 60
	s_nop 1
	v_writelane_b32 v254, s7, 61
	s_mov_b32 vcc_lo, 0
	s_nop 0
	v_writelane_b32 v255, vcc_lo, 40
	s_mov_b32 vcc_lo, -1
	s_nop 0
	v_writelane_b32 v255, vcc_lo, 49
	s_branch .LBB0_8

.Lnl_noinv:
	v_readlane_b32 s6, v255, 53
	v_readlane_b32 s7, v255, 54
	s_waitcnt lgkmcnt(0)
	s_nop 3
	global_load_dword v2, v131, s[6:7] sc1
	s_waitcnt vmcnt(0)
	v_cmp_eq_u32_e32 vcc, v2, v3
	s_and_saveexec_b64 s[6:7], vcc
	s_cbranch_execz .LBB0_40
	s_mov_b32 s13, 1
	s_mov_b64 s[10:11], 0
	s_branch .LBB0_31

.LBB0_33:
	v_readlane_b32 s24, v255, 53
	v_readlane_b32 s25, v255, 54
	s_add_i32 s13, s13, 1
	s_mov_b64 s[40:41], -1
	s_nop 2
	global_load_dword v2, v131, s[24:25] sc1
	s_waitcnt vmcnt(0)
	v_cmp_ne_u32_e32 vcc, v2, v3
	s_orn2_b64 s[38:39], vcc, exec
	s_branch .LBB0_30

.Lbar_local:
	s_waitcnt vmcnt(0) lgkmcnt(0)
	v_mov_b32_e32 v2, 1
	v_readlane_b32 s4, v253, 8
	v_readlane_b32 s5, v253, 9
	s_nop 4
	global_atomic_add v131, v2, s[4:5]
	v_mov_b32_e32 v3, 0x80
	global_atomic_add v3, v2, s[4:5]
	s_sub_u32 s4, s4, 0x1000
	s_subb_u32 s5, s5, 0
	global_atomic_add v3, v2, s[4:5]
	s_sub_u32 s4, s4, 0x1000
	s_subb_u32 s5, s5, 0
	global_atomic_add v3, v2, s[4:5]
	buffer_inv sc1
	s_waitcnt vmcnt(0)
	s_branch .LBB0_61

.LBB0_58:
	s_or_b64 exec, exec, s[4:5]
	s_mov_b64 s[4:5], exec
	v_mbcnt_lo_u32_b32 v2, s4, 0
	v_mbcnt_hi_u32_b32 v2, s5, v2
	v_cmp_eq_u32_e32 vcc, 0, v2
	s_waitcnt vmcnt(0)
	s_and_saveexec_b64 s[6:7], vcc
	s_cbranch_execz .LBB0_60
	s_bcnt1_i32_b64 s4, s[4:5]
	v_mov_b32_e32 v2, s4
	v_readlane_b32 s4, v253, 8
	v_readlane_b32 s5, v253, 9
	s_nop 4
	global_atomic_add v131, v2, s[4:5]
	v_mov_b32_e32 v3, 0x80
	global_atomic_add v3, v2, s[4:5]
	s_sub_u32 s4, s4, 0x1000
	s_subb_u32 s5, s5, 0
	global_atomic_add v3, v2, s[4:5]
	s_sub_u32 s4, s4, 0x1000
	s_subb_u32 s5, s5, 0
	global_atomic_add v3, v2, s[4:5]
